# strategy 2 on phase-1 RG-LRU weight-image convert loop (blocks 0..31): 16 serialized load-wait-store iterations replaced by 32 loads issued together, counted waits, then 32 stores; rest = v13
# baseline (speedup 1.0000x reference)
; __device__ __forceinline__ unsigned f2bf(float f) { return (unsigned)__builtin_bit_cast(unsigned short, (__bf16)f); }
; __device__ __forceinline__ void phase_convert(const Params& p, unsigned char* lds, const int part, const int wb0, const int nwb) {
;     ...
;         for (int m = (int)blockIdx.x - wb0; m < 32; m += nwb) { const float* src = ((m & 1) ? p.w_x : p.w_a) + (size_t)(m >> 1) * 16384; bf16_t* img = (bf16_t*)(p.ws + WS_LRUW) + (size_t)m * (128 * 136);
;             for (int e = threadIdx.x; e < 16384; e += 512) { const int ii = e >> 7, j = e & 127; img[j * 136 + ii] = (bf16_t)f2bf(src[e]); }
;             for (int e = threadIdx.x; e < 128 * 8; e += 512) img[(e >> 3) * 136 + 128 + (e & 7)] = (bf16_t)0; }
.LBB0_121:
	v_lshlrev_b32_e32 v232, 2, v162
	global_load_dword v200, v232, s[16:17]
	global_load_dword v201, v232, s[16:17] offset:2048
	v_add_u32_e32 v232, 0x1000, v232
	global_load_dword v202, v232, s[16:17]
	global_load_dword v203, v232, s[16:17] offset:2048
	v_add_u32_e32 v232, 0x1000, v232
	global_load_dword v204, v232, s[16:17]
	global_load_dword v205, v232, s[16:17] offset:2048
	v_add_u32_e32 v232, 0x1000, v232
	global_load_dword v206, v232, s[16:17]
	global_load_dword v207, v232, s[16:17] offset:2048
	v_add_u32_e32 v232, 0x1000, v232
	global_load_dword v208, v232, s[16:17]
	global_load_dword v209, v232, s[16:17] offset:2048
	v_add_u32_e32 v232, 0x1000, v232
	global_load_dword v210, v232, s[16:17]
	global_load_dword v211, v232, s[16:17] offset:2048
	v_add_u32_e32 v232, 0x1000, v232
	global_load_dword v212, v232, s[16:17]
	global_load_dword v213, v232, s[16:17] offset:2048
	v_add_u32_e32 v232, 0x1000, v232
	global_load_dword v214, v232, s[16:17]
	global_load_dword v215, v232, s[16:17] offset:2048
	v_add_u32_e32 v232, 0x1000, v232
	global_load_dword v216, v232, s[16:17]
	global_load_dword v217, v232, s[16:17] offset:2048
	v_add_u32_e32 v232, 0x1000, v232
	global_load_dword v218, v232, s[16:17]
	global_load_dword v219, v232, s[16:17] offset:2048
	v_add_u32_e32 v232, 0x1000, v232
	global_load_dword v220, v232, s[16:17]
	global_load_dword v221, v232, s[16:17] offset:2048
	v_add_u32_e32 v232, 0x1000, v232
	global_load_dword v222, v232, s[16:17]
	global_load_dword v223, v232, s[16:17] offset:2048
	v_add_u32_e32 v232, 0x1000, v232
	global_load_dword v224, v232, s[16:17]
	global_load_dword v225, v232, s[16:17] offset:2048
	v_add_u32_e32 v232, 0x1000, v232
	global_load_dword v226, v232, s[16:17]
	global_load_dword v227, v232, s[16:17] offset:2048
	v_add_u32_e32 v232, 0x1000, v232
	global_load_dword v228, v232, s[16:17]
	global_load_dword v229, v232, s[16:17] offset:2048
	v_add_u32_e32 v232, 0x1000, v232
	global_load_dword v230, v232, s[16:17]
	global_load_dword v231, v232, s[16:17] offset:2048
	v_lshrrev_b32_e32 v233, 7, v162
	v_add_lshl_u32 v233, v233, v0, 1
	s_waitcnt vmcnt(30)
	v_cvt_pk_bf16_f32 v200, v200, v201
	s_waitcnt vmcnt(28)
	v_cvt_pk_bf16_f32 v202, v202, v203
	s_waitcnt vmcnt(26)
	v_cvt_pk_bf16_f32 v204, v204, v205
	s_waitcnt vmcnt(24)
	v_cvt_pk_bf16_f32 v206, v206, v207
	s_waitcnt vmcnt(22)
	v_cvt_pk_bf16_f32 v208, v208, v209
	s_waitcnt vmcnt(20)
	v_cvt_pk_bf16_f32 v210, v210, v211
	s_waitcnt vmcnt(18)
	v_cvt_pk_bf16_f32 v212, v212, v213
	s_waitcnt vmcnt(16)
	v_cvt_pk_bf16_f32 v214, v214, v215
	s_waitcnt vmcnt(14)
	v_cvt_pk_bf16_f32 v216, v216, v217
	s_waitcnt vmcnt(12)
	v_cvt_pk_bf16_f32 v218, v218, v219
	s_waitcnt vmcnt(10)
	v_cvt_pk_bf16_f32 v220, v220, v221
	s_waitcnt vmcnt(8)
	v_cvt_pk_bf16_f32 v222, v222, v223
	s_waitcnt vmcnt(6)
	v_cvt_pk_bf16_f32 v224, v224, v225
	s_waitcnt vmcnt(4)
	v_cvt_pk_bf16_f32 v226, v226, v227
	s_waitcnt vmcnt(2)
	v_cvt_pk_bf16_f32 v228, v228, v229
	s_waitcnt vmcnt(0)
	v_cvt_pk_bf16_f32 v230, v230, v231
	global_store_short v233, v200, s[12:13]
	global_store_short_d16_hi v233, v200, s[12:13] offset:8
	global_store_short v233, v202, s[12:13] offset:16
	global_store_short_d16_hi v233, v202, s[12:13] offset:24
	global_store_short v233, v204, s[12:13] offset:32
	global_store_short_d16_hi v233, v204, s[12:13] offset:40
	global_store_short v233, v206, s[12:13] offset:48
	global_store_short_d16_hi v233, v206, s[12:13] offset:56
	global_store_short v233, v208, s[12:13] offset:64
	global_store_short_d16_hi v233, v208, s[12:13] offset:72
	global_store_short v233, v210, s[12:13] offset:80
	global_store_short_d16_hi v233, v210, s[12:13] offset:88
	global_store_short v233, v212, s[12:13] offset:96
	global_store_short_d16_hi v233, v212, s[12:13] offset:104
	global_store_short v233, v214, s[12:13] offset:112
	global_store_short_d16_hi v233, v214, s[12:13] offset:120
	global_store_short v233, v216, s[12:13] offset:128
	global_store_short_d16_hi v233, v216, s[12:13] offset:136
	global_store_short v233, v218, s[12:13] offset:144
	global_store_short_d16_hi v233, v218, s[12:13] offset:152
	global_store_short v233, v220, s[12:13] offset:160
	global_store_short_d16_hi v233, v220, s[12:13] offset:168
	global_store_short v233, v222, s[12:13] offset:176
	global_store_short_d16_hi v233, v222, s[12:13] offset:184
	global_store_short v233, v224, s[12:13] offset:192
	global_store_short_d16_hi v233, v224, s[12:13] offset:200
	global_store_short v233, v226, s[12:13] offset:208
	global_store_short_d16_hi v233, v226, s[12:13] offset:216
	global_store_short v233, v228, s[12:13] offset:224
	global_store_short_d16_hi v233, v228, s[12:13] offset:232
	global_store_short v233, v230, s[12:13] offset:240
	global_store_short_d16_hi v233, v230, s[12:13] offset:248
	s_or_b64 exec, exec, s[18:19]
	s_and_saveexec_b64 s[16:17], vcc
	s_cbranch_execz .LBB0_125
	v_lshl_add_u64 v[10:11], s[4:5], 0, v[6:7]
	v_lshl_add_u64 v[10:11], v[10:11], 0, s[14:15]
	s_mov_b64 s[4:5], 0
	v_mov_b32_e32 v8, v18
	v_mov_b32_e32 v12, v17
